# v8 + attention next-tile loads through scalar bases and 32-bit lane offsets (no per-tile address VALU)
# baseline (speedup 1.0000x reference)
; #define ATT_STORE(buf) do { _Pragma("unroll") for (int i_ = 0; i_ < 2; ++i_) { const int c_ = tid + 512 * i_; const int key_ = c_ >> 4, part_ = c_ & 15, e_ = c_ >> 3, vp_ = c_ & 7; \
;         *(LAS u32x4*)(lds + (buf) * KBYTES + (key_ * KP + part_ * 8) * 2) = kreg[i_]; \
;         *(LAS u32x4*)(lds + 3 * KBYTES + (buf) * VBYTES + (e_ * VP + vp_ * 8) * 2) = vreg[i_]; } } while (0)
; #define ATT_PV(bufv) do { \
;         const LAS bf16* Vb = (const LAS bf16*)(lds + 3 * KBYTES + (bufv) * VBYTES) + hi * 8; \
;         _Pragma("unroll") for (int es = 0; es < 4; ++es) _Pragma("unroll") for (int kk = 0; kk < 4; ++kk) { \
;             const bf16x8 a = *(const LAS bf16x8*)(Vb + (es * 32 + r32) * VP + kk * 16); O[es] = MFMA32(a, pf[kk], O[es]); } } while (0)
; DI void attn_unit(LAS unsigned char* lds, int tid, const bf16* __restrict__ P, const bf16* __restrict__ Vt, bf16* MG, int b, int h, int qrow0, int jt0, int jt1,
;                   float lam, float oscale, const float* subg) {
;     ...
;     __syncthreads();
;     ATT_LOADG(jt0);
;     int buf = 0, pbuf = 2;
;     for (int j = jt0; j < jt1; ++j) {
;         ATT_STORE(buf);
;         __syncthreads();
;         if (j + 1 < jt1) ATT_LOADG(j + 1);
;         if (!halfB) { ATT_QKS(buf, j == jt0); ATT_PV(buf); }
.LBB0_299:
	s_or_b64 exec, exec, s[2:3]
	s_lshl_b32 s17, s15, 7
	s_lshl_b32 s36, s17, 1
	s_mov_b64 s[40:41], s[36:37]
	v_writelane_b32 v253, s40, 6
	s_movk_i32 s15, 0x2200
	v_mad_i64_i32 v[102:103], s[2:3], v99, s15, 0
	v_writelane_b32 v253, s41, 7
	v_writelane_b32 v253, s42, 8
	v_mad_i64_i32 v[100:101], s[2:3], v100, s15, 0
	v_writelane_b32 v253, s43, 9
	s_bfe_u32 s2, s14, 0x10002
	v_writelane_b32 v253, s44, 10
	s_lshl_b32 s3, s2, 8
	v_writelane_b32 v253, s45, 11
	s_add_i32 s15, s9, s3
	s_lshl_b32 s3, s2, 12
	s_lshl_b32 s2, s2, 2
	v_writelane_b32 v253, s46, 12
	s_add_i32 s16, s12, s3
	s_add_i32 s2, s8, s2
	s_and_b32 s3, s13, 3
	v_writelane_b32 v253, s47, 13
	s_add_i32 s3, s2, s3
	v_writelane_b32 v253, s48, 14
	v_writelane_b32 v253, s49, 15
	s_add_u32 s18, s74, s36
	v_and_b32_e32 v177, 63, v98
	v_add_u32_e32 v178, v97, v176
	v_writelane_b32 v253, s50, 16
	s_addc_u32 s19, s75, 0
	v_mov_b32_e32 v97, v147
	v_and_b32_e32 v98, 7, v98
	v_writelane_b32 v253, s51, 17
	s_mov_b64 s[78:79], s[18:19]
	s_mov_b64 s[80:81], s[6:7]
	v_mul_lo_u32 v160, v155, s72
	v_mul_lo_u32 v161, v170, s72
	v_add_u32_e32 v160, v160, v96
	v_add_u32_e32 v161, v161, v96
	v_mad_i64_i32 v[96:97], s[18:19], s3, v217, v[102:103]
	v_lshlrev_b32_e32 v146, 4, v98
	v_writelane_b32 v253, s52, 18
	v_lshl_add_u64 v[96:97], v[96:97], 0, v[146:147]
	v_writelane_b32 v253, s53, 19
	v_mov_b32_e32 v162, v96
	v_mad_i64_i32 v[96:97], s[18:19], s3, v217, v[100:101]
	v_writelane_b32 v253, s54, 20
	v_lshl_add_u64 v[96:97], v[96:97], 0, v[146:147]
	v_ashrrev_i32_e32 v157, 31, v156
	v_add_f32_e32 v158, 0, v158
	s_mov_b32 s2, 1
	v_writelane_b32 v253, s55, 21
	v_mov_b32_e32 v164, v96
	s_mov_b32 s17, 0
	s_mov_b32 s21, 0
	s_mov_b32 s18, 1
	v_and_b32_e32 v209, 64, v210
	v_add_u32_e32 v209, 64, v209
	v_xor_b32_e32 v250, 32, v210
	v_cmp_lt_i32_e64 s[24:25], v250, v209
	s_nop 1
	v_cndmask_b32_e64 v209, v210, v250, s[24:25]
	v_lshlrev_b32_e32 v209, 2, v209
.LBB0_300:
	s_mov_b32 s19, s2
	s_mulk_i32 s2, 0x4400
	s_add_i32 s3, s2, 0
	s_lshl_b32 s20, s19, 10
	s_add_i32 s20, s3, s20
	v_add_u32_e32 v246, s3, v171
	v_add_u32_e32 v247, s20, v172
	s_waitcnt vmcnt(2)
	ds_write_b128 v246, v[132:135]
	s_waitcnt vmcnt(1)
	ds_write_b128 v247, v[128:131] offset:52224
	ds_write_b128 v246, v[136:139] offset:8704
	s_waitcnt vmcnt(0)
	ds_write_b128 v247, v[140:143] offset:61440
	v_add_u32_e32 v173, s2, v175
	s_mul_i32 s22, s21, 0x4800
	s_add_i32 s22, s22, 0xcc00
	v_add_u32_e32 v250, s22, v178
	ds_read_b128 v[188:191], v250
	ds_read_b128 v[192:195], v250 offset:4608
	ds_read_b128 v[196:199], v250 offset:9216
	ds_read_b128 v[200:203], v250 offset:13824
	ds_read_b128 v[204:207], v250 offset:32
	ds_read_b128 v[218:221], v250 offset:4640
	ds_read_b128 v[222:225], v250 offset:9248
	ds_read_b128 v[226:229], v250 offset:13856
	ds_read_b128 v[230:233], v250 offset:64
	ds_read_b128 v[234:237], v250 offset:4672
	ds_read_b128 v[238:241], v250 offset:9280
	s_cmp_eq_u32 s17, 0
	s_cbranch_scc1 .Latt1_first
	s_waitcnt lgkmcnt(10)
	v_mfma_f32_32x32x16_bf16 v[48:63], v[188:191], v[80:83], v[48:63]
	s_cmpk_lg_i32 s17, 0x1080
	s_cbranch_scc0 .Latt1_noload_a
	s_cmp_lt_u32 s18, 63
	s_cselect_b32 s3, s16, s15
	s_add_i32 s3, s3, s17
	s_mul_hi_i32 s23, s3, s72
	s_mul_i32 s22, s3, s72
	s_add_u32 s22, s22, s78
	s_addc_u32 s23, s23, s79
	global_load_dwordx4 v[128:131], v162, s[80:81]
	global_load_dwordx4 v[132:135], v160, s[22:23] offset:1024
	global_load_dwordx4 v[136:139], v161, s[22:23] offset:1024
	global_load_dwordx4 v[140:143], v164, s[80:81]

.Latt1_first:
	s_waitcnt lgkmcnt(10)
	v_mfma_f32_32x32x16_bf16 v[48:63], v[188:191], v[80:83], v[48:63]
	s_cmpk_lg_i32 s17, 0x1080
	s_cbranch_scc0 .Latt1_noload_b
	s_cmp_lt_u32 s18, 63
	s_cselect_b32 s3, s16, s15
	s_add_i32 s3, s3, s17
	s_mul_hi_i32 s23, s3, s72
	s_mul_i32 s22, s3, s72
	s_add_u32 s22, s22, s78
	s_addc_u32 s23, s23, s79
	global_load_dwordx4 v[128:131], v162, s[80:81]
	global_load_dwordx4 v[132:135], v160, s[22:23] offset:1024
	global_load_dwordx4 v[136:139], v161, s[22:23] offset:1024
	global_load_dwordx4 v[140:143], v164, s[80:81]

.Latt1_qk:
	s_waitcnt lgkmcnt(7)
	v_mfma_f32_32x32x16_bf16 v[80:95], v[192:195], v[112:115], v[64:79]
	s_waitcnt lgkmcnt(6)
	v_mfma_f32_32x32x16_bf16 v[96:111], v[196:199], v[112:115], v[64:79]
	s_waitcnt lgkmcnt(5)
	v_mfma_f32_32x32x16_bf16 v[80:95], v[200:203], v[116:119], v[80:95]
	s_waitcnt lgkmcnt(4)
	v_mfma_f32_32x32x16_bf16 v[96:111], v[204:207], v[116:119], v[96:111]
	s_waitcnt lgkmcnt(3)
	v_mfma_f32_32x32x16_bf16 v[80:95], v[218:221], v[120:123], v[80:95]
	s_waitcnt lgkmcnt(2)
	v_mfma_f32_32x32x16_bf16 v[96:111], v[222:225], v[120:123], v[96:111]
	s_waitcnt lgkmcnt(1)
	v_mfma_f32_32x32x16_bf16 v[80:95], v[226:229], v[124:127], v[80:95]
	s_waitcnt lgkmcnt(0)
	v_mfma_f32_32x32x16_bf16 v[96:111], v[230:233], v[124:127], v[96:111]
	s_add_i32 s2, s19, 1
	s_cmp_lg_u32 s19, 2
	s_cselect_b32 s2, s2, 0
	s_add_i32 s17, s17, 64
	s_add_u32 s80, s80, 0x80
	s_addc_u32 s81, s81, 0
	s_add_i32 s18, s18, 1
	s_nop 6
	v_max3_f32 v145, v80, v81, v82
	v_max3_f32 v146, v96, v97, v98
	v_max3_f32 v145, v145, v83, v84
	v_max3_f32 v146, v146, v99, v100
	v_max3_f32 v145, v145, v85, v86
	v_max3_f32 v146, v146, v101, v102
	v_max3_f32 v145, v145, v87, v88
	v_max3_f32 v146, v146, v103, v104
	v_max3_f32 v145, v145, v89, v90
	v_max3_f32 v146, v146, v105, v106
	v_max3_f32 v145, v145, v91, v92
	v_max3_f32 v146, v146, v107, v108
	v_max3_f32 v145, v145, v93, v94
	v_max3_f32 v146, v146, v109, v110
	v_max3_f32 v145, v145, v95, v111
	v_max_f32_e32 v145, v145, v146
	v_cmp_lt_f32_e32 vcc, 0x41000000, v145
	s_cbranch_vccz .Latt1_nors
	ds_bpermute_b32 v146, v209, v145
	s_waitcnt lgkmcnt(0)
	v_max_f32_e32 v146, v145, v146
	v_cmp_lt_f32_e32 vcc, 0x41000000, v146
	s_nop 0
	s_nop 0
	v_cndmask_b32_e32 v146, 0, v146, vcc
	v_exp_f32_e64 v150, -v146
	v_add_f32_e32 v159, v159, v146
	v_xor_b32_e32 v64, 0x80000000, v159
	v_mov_b32_e32 v65, v64
	v_mov_b32_e32 v66, v64
	v_mov_b32_e32 v67, v64
	v_mov_b32_e32 v68, v64
	v_mov_b32_e32 v69, v64
	v_mov_b32_e32 v70, v64
	v_mov_b32_e32 v71, v64
	v_mov_b32_e32 v72, v64
	v_mov_b32_e32 v73, v64
	v_mov_b32_e32 v74, v64
	v_mov_b32_e32 v75, v64
	v_mov_b32_e32 v76, v64
	v_mov_b32_e32 v77, v64
	v_mov_b32_e32 v78, v64
	v_mov_b32_e32 v79, v64
	v_mul_f32_e32 v158, v158, v150
	v_pk_mul_f32 v[14:15], v[14:15], v[150:151] op_sel_hi:[1,0]
	v_pk_mul_f32 v[12:13], v[12:13], v[150:151] op_sel_hi:[1,0]
	v_pk_mul_f32 v[10:11], v[10:11], v[150:151] op_sel_hi:[1,0]
	v_pk_mul_f32 v[8:9], v[8:9], v[150:151] op_sel_hi:[1,0]
	v_pk_mul_f32 v[6:7], v[6:7], v[150:151] op_sel_hi:[1,0]
	v_pk_mul_f32 v[4:5], v[4:5], v[150:151] op_sel_hi:[1,0]
	v_pk_mul_f32 v[2:3], v[2:3], v[150:151] op_sel_hi:[1,0]
	v_pk_mul_f32 v[0:1], v[0:1], v[150:151] op_sel_hi:[1,0]
	v_pk_mul_f32 v[30:31], v[30:31], v[150:151] op_sel_hi:[1,0]
	v_pk_mul_f32 v[28:29], v[28:29], v[150:151] op_sel_hi:[1,0]
	v_pk_mul_f32 v[26:27], v[26:27], v[150:151] op_sel_hi:[1,0]
	v_pk_mul_f32 v[24:25], v[24:25], v[150:151] op_sel_hi:[1,0]
	v_pk_mul_f32 v[22:23], v[22:23], v[150:151] op_sel_hi:[1,0]
	v_pk_mul_f32 v[20:21], v[20:21], v[150:151] op_sel_hi:[1,0]
	v_pk_mul_f32 v[18:19], v[18:19], v[150:151] op_sel_hi:[1,0]
	v_pk_mul_f32 v[16:17], v[16:17], v[150:151] op_sel_hi:[1,0]
	v_pk_mul_f32 v[46:47], v[46:47], v[150:151] op_sel_hi:[1,0]
	v_pk_mul_f32 v[44:45], v[44:45], v[150:151] op_sel_hi:[1,0]
	v_pk_mul_f32 v[42:43], v[42:43], v[150:151] op_sel_hi:[1,0]
	v_pk_mul_f32 v[40:41], v[40:41], v[150:151] op_sel_hi:[1,0]
	v_pk_mul_f32 v[38:39], v[38:39], v[150:151] op_sel_hi:[1,0]
	v_pk_mul_f32 v[36:37], v[36:37], v[150:151] op_sel_hi:[1,0]
	v_pk_mul_f32 v[34:35], v[34:35], v[150:151] op_sel_hi:[1,0]
	v_pk_mul_f32 v[32:33], v[32:33], v[150:151] op_sel_hi:[1,0]
	v_pk_mul_f32 v[62:63], v[62:63], v[150:151] op_sel_hi:[1,0]
	v_pk_mul_f32 v[60:61], v[60:61], v[150:151] op_sel_hi:[1,0]
	v_pk_mul_f32 v[58:59], v[58:59], v[150:151] op_sel_hi:[1,0]
	v_pk_mul_f32 v[56:57], v[56:57], v[150:151] op_sel_hi:[1,0]
	v_pk_mul_f32 v[54:55], v[54:55], v[150:151] op_sel_hi:[1,0]
	v_pk_mul_f32 v[52:53], v[52:53], v[150:151] op_sel_hi:[1,0]
	v_pk_mul_f32 v[50:51], v[50:51], v[150:151] op_sel_hi:[1,0]
	v_pk_mul_f32 v[48:49], v[48:49], v[150:151] op_sel_hi:[1,0]
	v_pk_add_f32 v[80:81], v[80:81], v[146:147] op_sel_hi:[1,0] neg_lo:[0,1] neg_hi:[0,1]
	v_pk_add_f32 v[96:97], v[96:97], v[146:147] op_sel_hi:[1,0] neg_lo:[0,1] neg_hi:[0,1]
	v_pk_add_f32 v[82:83], v[82:83], v[146:147] op_sel_hi:[1,0] neg_lo:[0,1] neg_hi:[0,1]
	v_pk_add_f32 v[98:99], v[98:99], v[146:147] op_sel_hi:[1,0] neg_lo:[0,1] neg_hi:[0,1]
	v_pk_add_f32 v[84:85], v[84:85], v[146:147] op_sel_hi:[1,0] neg_lo:[0,1] neg_hi:[0,1]
	v_pk_add_f32 v[100:101], v[100:101], v[146:147] op_sel_hi:[1,0] neg_lo:[0,1] neg_hi:[0,1]
	v_pk_add_f32 v[86:87], v[86:87], v[146:147] op_sel_hi:[1,0] neg_lo:[0,1] neg_hi:[0,1]
	v_pk_add_f32 v[102:103], v[102:103], v[146:147] op_sel_hi:[1,0] neg_lo:[0,1] neg_hi:[0,1]
	v_pk_add_f32 v[88:89], v[88:89], v[146:147] op_sel_hi:[1,0] neg_lo:[0,1] neg_hi:[0,1]
	v_pk_add_f32 v[104:105], v[104:105], v[146:147] op_sel_hi:[1,0] neg_lo:[0,1] neg_hi:[0,1]
	v_pk_add_f32 v[90:91], v[90:91], v[146:147] op_sel_hi:[1,0] neg_lo:[0,1] neg_hi:[0,1]
	v_pk_add_f32 v[106:107], v[106:107], v[146:147] op_sel_hi:[1,0] neg_lo:[0,1] neg_hi:[0,1]
	v_pk_add_f32 v[92:93], v[92:93], v[146:147] op_sel_hi:[1,0] neg_lo:[0,1] neg_hi:[0,1]
	v_pk_add_f32 v[108:109], v[108:109], v[146:147] op_sel_hi:[1,0] neg_lo:[0,1] neg_hi:[0,1]
	v_pk_add_f32 v[94:95], v[94:95], v[146:147] op_sel_hi:[1,0] neg_lo:[0,1] neg_hi:[0,1]
	v_pk_add_f32 v[110:111], v[110:111], v[146:147] op_sel_hi:[1,0] neg_lo:[0,1] neg_hi:[0,1]
